# HGRN output phase inner loop: LDS fragment reads of the two MFMA chains run ahead of the MFMAs with counted lgkmcnt waits (was one LDS round trip per MFMA)
# baseline (speedup 1.0000x reference)
; template <bool OUT>
; __device__ __forceinline__ void hgrn_pass(Frame& F, int b, int h, int dir, int sc, f32x16 (&st)[2], float& dsum, float& dsum2) {
;     ...
;         if (OUT) {
;             f32x16 oacc;
; #pragma unroll
;             for (int r = 0; r < 16; ++r) oacc[r] = 0.f;
;             const LAS unsigned char* qrow = L + HG_QT + (32 * jb + r32) * 272 + hh * 16;
;             const LAS unsigned char* srow = L + HG_ST + (32 * dvb + r32) * 272 + hh * 16;
;             const LAS unsigned char* vrow = L + HG_VT + (32 * dvb + r32) * 144 + hh * 16;
; #pragma unroll
;             for (int ks = 0; ks < 8; ++ks) oacc = __builtin_amdgcn_mfma_f32_32x32x16_bf16(*(const LAS bf16x8_t*)(qrow + ks * 32), *(const LAS bf16x8_t*)(srow + ks * 32), oacc, 0, 0, 0);
;             {
;                 f32x16 at;
; #pragma unroll
;                 for (int r = 0; r < 16; ++r) at[r] = 0.f;
;                 const LAS unsigned char* krow = L + HG_KT + r32 * 272 + hh * 16;
; #pragma unroll
;                 for (int ks = 0; ks < 8; ++ks) at = __builtin_amdgcn_mfma_f32_32x32x16_bf16(*(const LAS bf16x8_t*)(krow + ks * 32), *(const LAS bf16x8_t*)(qrow + ks * 32), at, 0, 0, 0);
;                 if (jb == 0) {
; #pragma unroll
;                     for (int r = 0; r < 16; ++r) if (crow(r, hh) > r32) at[r] = 0.f; }
;                 oacc = __builtin_amdgcn_mfma_f32_32x32x16_bf16(pack_frag(at, 0), *(const LAS bf16x8_t*)(vrow + 0), oacc, 0, 0, 0);
;                 oacc = __builtin_amdgcn_mfma_f32_32x32x16_bf16(pack_frag(at, 8), *(const LAS bf16x8_t*)(vrow + 32), oacc, 0, 0, 0);
;             }
;             if (jb == 1) {
;                 f32x16 at;
; #pragma unroll
;                 for (int r = 0; r < 16; ++r) at[r] = 0.f;
;                 const LAS unsigned char* krow = L + HG_KT + (32 + r32) * 272 + hh * 16;
; #pragma unroll
;                 for (int ks = 0; ks < 8; ++ks) at = __builtin_amdgcn_mfma_f32_32x32x16_bf16(*(const LAS bf16x8_t*)(krow + ks * 32), *(const LAS bf16x8_t*)(qrow + ks * 32), at, 0, 0, 0);
; #pragma unroll
;                 for (int r = 0; r < 16; ++r) if (crow(r, hh) > r32) at[r] = 0.f;
;                 oacc = __builtin_amdgcn_mfma_f32_32x32x16_bf16(pack_frag(at, 0), *(const LAS bf16x8_t*)(vrow + 64), oacc, 0, 0, 0);
;                 oacc = __builtin_amdgcn_mfma_f32_32x32x16_bf16(pack_frag(at, 8), *(const LAS bf16x8_t*)(vrow + 96), oacc, 0, 0, 0);
.LBB0_2418:
	s_waitcnt lgkmcnt(0)
	s_barrier
	v_add_u32_e32 v79, v1, v147
	s_andn2_b64 vcc, exec, s[66:67]
	ds_read_b128 v[50:53], v191
	ds_read_b128 v[34:37], v79
	ds_read_b128 v[122:125], v191 offset:32
	ds_read_b128 v[54:57], v79 offset:32
	ds_read_b128 v[126:129], v191 offset:64
	ds_read_b128 v[228:231], v79 offset:64
	ds_read_b128 v[130:133], v191 offset:96
	ds_read_b128 v[58:61], v79 offset:96
	ds_read_b128 v[134:137], v191 offset:128
	ds_read_b128 v[244:247], v79 offset:128
	ds_read_b128 v[138:141], v191 offset:160
	ds_read_b128 v[62:65], v79 offset:160
	ds_read_b128 v[220:223], v191 offset:192
	ds_read_b128 v[248:251], v79 offset:192
	s_waitcnt lgkmcnt(12)
	v_mfma_f32_32x32x16_bf16 v[34:49], v[50:53], v[34:37], 0
	ds_read_b128 v[240:243], v192 offset:17408
	ds_read_b128 v[224:227], v192 offset:17440
	s_waitcnt lgkmcnt(12)
	v_mfma_f32_32x32x16_bf16 v[34:49], v[122:125], v[54:57], v[34:49]
	s_waitcnt lgkmcnt(10)
	v_mfma_f32_32x32x16_bf16 v[34:49], v[126:129], v[228:231], v[34:49]
	s_waitcnt lgkmcnt(8)
	v_mfma_f32_32x32x16_bf16 v[34:49], v[130:133], v[58:61], v[34:49]
	s_waitcnt lgkmcnt(6)
	v_mfma_f32_32x32x16_bf16 v[34:49], v[134:137], v[244:247], v[34:49]
	s_waitcnt lgkmcnt(4)
	v_mfma_f32_32x32x16_bf16 v[34:49], v[138:141], v[62:65], v[34:49]
	s_waitcnt lgkmcnt(2)
	v_mfma_f32_32x32x16_bf16 v[34:49], v[220:223], v[248:251], v[34:49]
	s_waitcnt lgkmcnt(1)
	v_mfma_f32_32x32x16_bf16 v[50:65], v[240:243], v[50:53], 0
	ds_read_b128 v[240:243], v192 offset:17472
	s_waitcnt lgkmcnt(1)
	v_mfma_f32_32x32x16_bf16 v[50:65], v[224:227], v[122:125], v[50:65]
	ds_read_b128 v[224:227], v192 offset:17504
	ds_read_b128 v[122:125], v79 offset:224
	s_waitcnt lgkmcnt(2)
	v_mfma_f32_32x32x16_bf16 v[50:65], v[240:243], v[126:129], v[50:65]
	ds_read_b128 v[240:243], v192 offset:17536
	ds_read_b128 v[126:129], v191 offset:224
	s_waitcnt lgkmcnt(3)
	v_mfma_f32_32x32x16_bf16 v[50:65], v[224:227], v[130:133], v[50:65]
	ds_read_b128 v[224:227], v192 offset:17568
	s_waitcnt lgkmcnt(2)
	v_mfma_f32_32x32x16_bf16 v[50:65], v[240:243], v[134:137], v[50:65]
	ds_read_b128 v[240:243], v192 offset:17600
	s_waitcnt lgkmcnt(1)
	v_mfma_f32_32x32x16_bf16 v[50:65], v[224:227], v[138:141], v[50:65]
	ds_read_b128 v[224:227], v192 offset:17632
	s_waitcnt lgkmcnt(1)
	v_mfma_f32_32x32x16_bf16 v[50:65], v[240:243], v[220:223], v[50:65]
	s_waitcnt lgkmcnt(0)
	v_mfma_f32_32x32x16_bf16 v[50:65], v[224:227], v[126:129], v[50:65]
	s_waitcnt lgkmcnt(3)
	v_mfma_f32_32x32x16_bf16 v[34:49], v[126:129], v[122:125], v[34:49]
	s_cbranch_vccnz .LBB0_2420
	s_nop 7
	v_cndmask_b32_e64 v79, v50, 0, s[20:21]
	v_cndmask_b32_e64 v51, 0, v51, s[22:23]
	v_cndmask_b32_e64 v50, v79, v50, s[22:23]
	v_cndmask_b32_e64 v52, v52, 0, s[24:25]
	v_cndmask_b32_e64 v53, v53, 0, s[26:27]
	v_cndmask_b32_e64 v54, v54, 0, s[28:29]
	v_cndmask_b32_e64 v55, v55, 0, s[30:31]
	v_cndmask_b32_e64 v56, v56, 0, s[34:35]
	v_cndmask_b32_e64 v57, v57, 0, s[36:37]
	v_cndmask_b32_e64 v58, v58, 0, s[38:39]
	v_cndmask_b32_e64 v59, v59, 0, s[40:41]
	v_cndmask_b32_e64 v60, v60, 0, s[42:43]
	v_cndmask_b32_e64 v61, v61, 0, s[44:45]
	v_cndmask_b32_e64 v62, v62, 0, s[46:47]
	v_cndmask_b32_e64 v63, v63, 0, s[48:49]
	v_cndmask_b32_e64 v64, v64, 0, s[50:51]
	v_cndmask_b32_e64 v65, v65, 0, s[52:53]
.LBB0_2420:
	v_cvt_pk_bf16_f32 v50, v50, v51
	v_cvt_pk_bf16_f32 v51, v52, v53
	v_cvt_pk_bf16_f32 v52, v54, v55
	v_cvt_pk_bf16_f32 v53, v56, v57
	s_nop 7
	ds_read_b128 v[54:57], v193 offset:53248
	s_waitcnt lgkmcnt(0)
	v_mfma_f32_32x32x16_bf16 v[34:49], v[50:53], v[54:57], v[34:49]
	v_cvt_pk_bf16_f32 v50, v58, v59
	v_cvt_pk_bf16_f32 v51, v60, v61
	v_cvt_pk_bf16_f32 v52, v62, v63
	v_cvt_pk_bf16_f32 v53, v64, v65
	ds_read_b128 v[54:57], v193 offset:53280
	s_andn2_b64 vcc, exec, s[68:69]
	s_waitcnt lgkmcnt(0)
	v_mfma_f32_32x32x16_bf16 v[34:49], v[50:53], v[54:57], v[34:49]
	s_cbranch_vccnz .LBB0_2422
	ds_read_b128 v[50:53], v192 offset:26112
	ds_read_b128 v[54:57], v191
	ds_read_b128 v[122:125], v192 offset:26144
	ds_read_b128 v[126:129], v191 offset:32
	ds_read_b128 v[240:243], v192 offset:26176
	ds_read_b128 v[244:247], v191 offset:64
	ds_read_b128 v[228:231], v192 offset:26208
	ds_read_b128 v[248:251], v191 offset:96
	s_waitcnt lgkmcnt(6)
	v_mfma_f32_32x32x16_bf16 v[50:65], v[50:53], v[54:57], 0
	s_waitcnt lgkmcnt(4)
	v_mfma_f32_32x32x16_bf16 v[50:65], v[122:125], v[126:129], v[50:65]
	ds_read_b128 v[122:125], v192 offset:26240
	ds_read_b128 v[126:129], v191 offset:128
	s_waitcnt lgkmcnt(4)
	v_mfma_f32_32x32x16_bf16 v[50:65], v[240:243], v[244:247], v[50:65]
	ds_read_b128 v[240:243], v192 offset:26272
	ds_read_b128 v[244:247], v191 offset:160
	s_waitcnt lgkmcnt(4)
	v_mfma_f32_32x32x16_bf16 v[50:65], v[228:231], v[248:251], v[50:65]
	ds_read_b128 v[228:231], v192 offset:26304
	ds_read_b128 v[248:251], v191 offset:192
	s_waitcnt lgkmcnt(4)
	v_mfma_f32_32x32x16_bf16 v[50:65], v[122:125], v[126:129], v[50:65]
	ds_read_b128 v[122:125], v192 offset:26336
	ds_read_b128 v[126:129], v191 offset:224
	s_waitcnt lgkmcnt(4)
	v_mfma_f32_32x32x16_bf16 v[50:65], v[240:243], v[244:247], v[50:65]
	s_waitcnt lgkmcnt(2)
	v_mfma_f32_32x32x16_bf16 v[50:65], v[228:231], v[248:251], v[50:65]
	s_waitcnt lgkmcnt(0)
	v_mfma_f32_32x32x16_bf16 v[50:65], v[122:125], v[126:129], v[50:65]
	s_nop 11
	v_cndmask_b32_e64 v79, v50, 0, s[20:21]
	v_cndmask_b32_e64 v51, 0, v51, s[22:23]
	v_cndmask_b32_e64 v52, v52, 0, s[24:25]
	v_cndmask_b32_e64 v53, v53, 0, s[26:27]
	v_cndmask_b32_e64 v54, v54, 0, s[28:29]
	v_cndmask_b32_e64 v55, v55, 0, s[30:31]
	v_cndmask_b32_e64 v56, v56, 0, s[34:35]
	v_cndmask_b32_e64 v57, v57, 0, s[36:37]
	v_cndmask_b32_e64 v50, v79, v50, s[22:23]
	v_cvt_pk_bf16_f32 v50, v50, v51
	v_cvt_pk_bf16_f32 v51, v52, v53
	v_cvt_pk_bf16_f32 v52, v54, v55
	v_cvt_pk_bf16_f32 v53, v56, v57
	ds_read_b128 v[54:57], v193 offset:53312
	s_waitcnt lgkmcnt(0)
	v_mfma_f32_32x32x16_bf16 v[34:49], v[50:53], v[54:57], v[34:49]
	v_cndmask_b32_e64 v58, v58, 0, s[38:39]
	v_cndmask_b32_e64 v59, v59, 0, s[40:41]
	v_cndmask_b32_e64 v60, v60, 0, s[42:43]
	v_cndmask_b32_e64 v61, v61, 0, s[44:45]
	v_cndmask_b32_e64 v62, v62, 0, s[46:47]
	v_cndmask_b32_e64 v63, v63, 0, s[48:49]
	v_cndmask_b32_e64 v64, v64, 0, s[50:51]
	v_cndmask_b32_e64 v65, v65, 0, s[52:53]
	v_cvt_pk_bf16_f32 v58, v58, v59
	v_cvt_pk_bf16_f32 v59, v60, v61
	v_cvt_pk_bf16_f32 v60, v62, v63
	v_cvt_pk_bf16_f32 v61, v64, v65
	ds_read_b128 v[50:53], v193 offset:53344
	s_waitcnt lgkmcnt(0)
	v_mfma_f32_32x32x16_bf16 v[34:49], v[58:61], v[50:53], v[34:49]
